# counted vmcnt in MLA prompt flash loop (strip in-loop qf vmcnt waits, vmcnt(4) before stage store)
# baseline (speedup 1.0000x reference)
.LBB0_954:
	s_and_b32 s92, s69, 1
	s_cmp_gt_i32 s69, s50
	s_cbranch_scc1 .LBB0_959
	s_mul_i32 s4, s92, 0x5400
	s_add_i32 s24, s4, 0
	v_add3_u32 v153, s24, v192, v142
	ds_read_b128 v[32:35], v153
	ds_read_b128 v[36:39], v153 offset:32
	s_waitcnt lgkmcnt(1)
	v_mfma_f32_32x32x16_bf16 v[48:63], v[32:35], v[64:67], 0
	s_waitcnt lgkmcnt(0)
	v_mfma_f32_32x32x16_bf16 v[48:63], v[36:39], v[68:71], v[48:63]
	ds_read_b128 v[32:35], v153 offset:64
	ds_read_b128 v[36:39], v153 offset:96
	s_waitcnt lgkmcnt(1)
	v_mfma_f32_32x32x16_bf16 v[48:63], v[32:35], v[72:75], v[48:63]
	s_waitcnt lgkmcnt(0)
	v_mfma_f32_32x32x16_bf16 v[48:63], v[36:39], v[76:79], v[48:63]
	ds_read_b128 v[32:35], v153 offset:256
	ds_read_b128 v[36:39], v153 offset:288
	s_waitcnt lgkmcnt(1)
	v_mfma_f32_32x32x16_bf16 v[48:63], v[32:35], v[80:83], v[48:63]
	ds_read_b128 v[32:35], v153 offset:10752
	ds_read_b128 v[154:157], v153 offset:10784
	s_waitcnt lgkmcnt(2)
	v_mfma_f32_32x32x16_bf16 v[48:63], v[36:39], v[84:87], v[48:63]
	s_waitcnt lgkmcnt(1)
	v_mfma_f32_32x32x16_bf16 v[32:47], v[32:35], v[64:67], 0
	s_nop 9
	v_max_f32_e32 v162, v48, v48
	s_waitcnt lgkmcnt(0)
	v_mfma_f32_32x32x16_bf16 v[32:47], v[154:157], v[68:71], v[32:47]
	ds_read_b128 v[154:157], v153 offset:10816
	ds_read_b128 v[158:161], v153 offset:10848
	s_waitcnt lgkmcnt(1)
	v_mfma_f32_32x32x16_bf16 v[32:47], v[154:157], v[72:75], v[32:47]
	s_waitcnt lgkmcnt(0)
	v_mfma_f32_32x32x16_bf16 v[32:47], v[158:161], v[76:79], v[32:47]
	ds_read_b128 v[154:157], v153 offset:11008
	ds_read_b128 v[158:161], v153 offset:11040
	v_max_f32_e32 v153, v49, v49
	v_max_f32_e32 v153, v162, v153
	v_max3_f32 v153, v153, v50, v51
	v_max3_f32 v153, v153, v52, v53
	v_max3_f32 v153, v153, v54, v55
	v_max3_f32 v153, v153, v56, v57
	s_waitcnt lgkmcnt(1)
	v_mfma_f32_32x32x16_bf16 v[32:47], v[154:157], v[80:83], v[32:47]
	v_max3_f32 v153, v153, v58, v59
	v_max3_f32 v153, v153, v60, v61
	v_max3_f32 v153, v153, v62, v63
	s_waitcnt lgkmcnt(0)
	v_mfma_f32_32x32x16_bf16 v[32:47], v[158:161], v[84:87], v[32:47]
	s_nop 11
	v_max3_f32 v153, v153, v32, v33
	v_max3_f32 v153, v153, v34, v35
	v_max3_f32 v153, v153, v36, v37
	v_max3_f32 v153, v153, v38, v39
	v_max3_f32 v153, v153, v40, v41
	v_max3_f32 v153, v153, v42, v43
	v_max3_f32 v153, v153, v44, v45
	v_max3_f32 v153, v153, v46, v47
	v_mov_b32_e32 v154, v153
	s_nop 1
	v_permlane32_swap_b32_e32 v153, v154
	v_max_f32_e32 v154, v154, v154
	v_max_f32_e32 v153, v153, v153
	v_max_f32_e32 v153, v153, v154
	v_cmp_gt_f32_e32 vcc, v153, v152
	s_cbranch_vccz .LBB0_957
	v_max_f32_e32 v153, v153, v153
	v_max_f32_e32 v154, v152, v152
	v_max_f32_e32 v153, v154, v153
	v_sub_f32_e32 v152, v152, v153
	v_exp_f32_e32 v152, v152
	s_nop 0
	v_pk_mul_f32 v[30:31], v[30:31], v[152:153] op_sel_hi:[1,0]
	v_pk_mul_f32 v[28:29], v[28:29], v[152:153] op_sel_hi:[1,0]
	v_pk_mul_f32 v[26:27], v[26:27], v[152:153] op_sel_hi:[1,0]
	v_pk_mul_f32 v[24:25], v[24:25], v[152:153] op_sel_hi:[1,0]
	v_pk_mul_f32 v[22:23], v[22:23], v[152:153] op_sel_hi:[1,0]
	v_pk_mul_f32 v[20:21], v[20:21], v[152:153] op_sel_hi:[1,0]
	v_pk_mul_f32 v[18:19], v[18:19], v[152:153] op_sel_hi:[1,0]
	v_pk_mul_f32 v[16:17], v[16:17], v[152:153] op_sel_hi:[1,0]
	v_pk_mul_f32 v[14:15], v[14:15], v[152:153] op_sel_hi:[1,0]
	v_pk_mul_f32 v[12:13], v[12:13], v[152:153] op_sel_hi:[1,0]
	v_pk_mul_f32 v[10:11], v[10:11], v[152:153] op_sel_hi:[1,0]
	v_pk_mul_f32 v[8:9], v[8:9], v[152:153] op_sel_hi:[1,0]
	v_pk_mul_f32 v[6:7], v[6:7], v[152:153] op_sel_hi:[1,0]
	v_pk_mul_f32 v[4:5], v[4:5], v[152:153] op_sel_hi:[1,0]
	v_pk_mul_f32 v[2:3], v[2:3], v[152:153] op_sel_hi:[1,0]
	v_pk_mul_f32 v[0:1], v[0:1], v[152:153] op_sel_hi:[1,0]
	v_mul_f32_e32 v151, v151, v152
	v_mov_b32_e32 v152, v153

.LBB0_960:
	s_xor_b32 s4, s92, 1
	s_mulk_i32 s4, 0x5400
	s_add_i32 s4, s4, 0
	s_cmp_le_u32 s69, s60
	s_cbranch_scc0 .Lfl1_tail_a
	s_waitcnt vmcnt(4)
	s_branch .Lfl1_go_a

.Lfl1_go_a:
	s_and_saveexec_b64 s[66:67], s[8:9]
	s_cbranch_execz .LBB0_977
	v_add3_u32 v32, s4, v144, v145
	ds_write_b128 v32, v[100:103]
	s_or_b64 exec, exec, s[66:67]
	s_and_saveexec_b64 s[66:67], s[10:11]
	s_cbranch_execnz .LBB0_978

.LBB0_963:
	v_add3_u32 v32, s4, v149, v150
	ds_write_b128 v32, v[108:111]

.LBB0_970:
	s_add_i32 s93, s69, 1
	s_cmp_ge_u32 s93, s47
	s_waitcnt lgkmcnt(0)
	s_barrier
	s_cbranch_scc1 .LBB0_976
	s_and_b32 s66, s93, 1
	s_cmp_ge_i32 s69, s50
	s_cbranch_scc1 .LBB0_981
	s_mul_i32 s4, s66, 0x5400
	s_add_i32 s24, s4, 0
	v_add3_u32 v153, s24, v192, v142
	ds_read_b128 v[32:35], v153
	ds_read_b128 v[36:39], v153 offset:32
	s_waitcnt lgkmcnt(1)
	v_mfma_f32_32x32x16_bf16 v[48:63], v[32:35], v[64:67], 0
	s_waitcnt lgkmcnt(0)
	v_mfma_f32_32x32x16_bf16 v[48:63], v[36:39], v[68:71], v[48:63]
	ds_read_b128 v[32:35], v153 offset:64
	ds_read_b128 v[36:39], v153 offset:96
	s_waitcnt lgkmcnt(1)
	v_mfma_f32_32x32x16_bf16 v[48:63], v[32:35], v[72:75], v[48:63]
	s_waitcnt lgkmcnt(0)
	v_mfma_f32_32x32x16_bf16 v[48:63], v[36:39], v[76:79], v[48:63]
	ds_read_b128 v[32:35], v153 offset:256
	ds_read_b128 v[36:39], v153 offset:288
	s_waitcnt lgkmcnt(1)
	v_mfma_f32_32x32x16_bf16 v[48:63], v[32:35], v[80:83], v[48:63]
	ds_read_b128 v[32:35], v153 offset:10752
	ds_read_b128 v[154:157], v153 offset:10784
	s_waitcnt lgkmcnt(2)
	v_mfma_f32_32x32x16_bf16 v[48:63], v[36:39], v[84:87], v[48:63]
	s_waitcnt lgkmcnt(1)
	v_mfma_f32_32x32x16_bf16 v[32:47], v[32:35], v[64:67], 0
	s_nop 9
	v_max_f32_e32 v162, v48, v48
	s_waitcnt lgkmcnt(0)
	v_mfma_f32_32x32x16_bf16 v[32:47], v[154:157], v[68:71], v[32:47]
	ds_read_b128 v[154:157], v153 offset:10816
	ds_read_b128 v[158:161], v153 offset:10848
	s_waitcnt lgkmcnt(1)
	v_mfma_f32_32x32x16_bf16 v[32:47], v[154:157], v[72:75], v[32:47]
	s_waitcnt lgkmcnt(0)
	v_mfma_f32_32x32x16_bf16 v[32:47], v[158:161], v[76:79], v[32:47]
	ds_read_b128 v[154:157], v153 offset:11008
	ds_read_b128 v[158:161], v153 offset:11040
	v_max_f32_e32 v153, v49, v49
	v_max_f32_e32 v153, v162, v153
	v_max3_f32 v153, v153, v50, v51
	v_max3_f32 v153, v153, v52, v53
	v_max3_f32 v153, v153, v54, v55
	v_max3_f32 v153, v153, v56, v57
	s_waitcnt lgkmcnt(1)
	v_mfma_f32_32x32x16_bf16 v[32:47], v[154:157], v[80:83], v[32:47]
	v_max3_f32 v153, v153, v58, v59
	v_max3_f32 v153, v153, v60, v61
	v_max3_f32 v153, v153, v62, v63
	s_waitcnt lgkmcnt(0)
	v_mfma_f32_32x32x16_bf16 v[32:47], v[158:161], v[84:87], v[32:47]
	s_nop 11
	v_max3_f32 v153, v153, v32, v33
	v_max3_f32 v153, v153, v34, v35
	v_max3_f32 v153, v153, v36, v37
	v_max3_f32 v153, v153, v38, v39
	v_max3_f32 v153, v153, v40, v41
	v_max3_f32 v153, v153, v42, v43
	v_max3_f32 v153, v153, v44, v45
	v_max3_f32 v153, v153, v46, v47
	v_mov_b32_e32 v154, v153
	s_nop 1
	v_permlane32_swap_b32_e32 v153, v154
	v_max_f32_e32 v154, v154, v154
	v_max_f32_e32 v153, v153, v153
	v_max_f32_e32 v153, v153, v154
	v_cmp_gt_f32_e32 vcc, v153, v152
	s_cbranch_vccz .LBB0_974
	v_max_f32_e32 v153, v153, v153
	v_max_f32_e32 v154, v152, v152
	v_max_f32_e32 v153, v154, v153
	v_sub_f32_e32 v152, v152, v153
	v_exp_f32_e32 v152, v152
	s_nop 0
	v_pk_mul_f32 v[30:31], v[30:31], v[152:153] op_sel_hi:[1,0]
	v_pk_mul_f32 v[28:29], v[28:29], v[152:153] op_sel_hi:[1,0]
	v_pk_mul_f32 v[26:27], v[26:27], v[152:153] op_sel_hi:[1,0]
	v_pk_mul_f32 v[24:25], v[24:25], v[152:153] op_sel_hi:[1,0]
	v_pk_mul_f32 v[22:23], v[22:23], v[152:153] op_sel_hi:[1,0]
	v_pk_mul_f32 v[20:21], v[20:21], v[152:153] op_sel_hi:[1,0]
	v_pk_mul_f32 v[18:19], v[18:19], v[152:153] op_sel_hi:[1,0]
	v_pk_mul_f32 v[16:17], v[16:17], v[152:153] op_sel_hi:[1,0]
	v_pk_mul_f32 v[14:15], v[14:15], v[152:153] op_sel_hi:[1,0]
	v_pk_mul_f32 v[12:13], v[12:13], v[152:153] op_sel_hi:[1,0]
	v_pk_mul_f32 v[10:11], v[10:11], v[152:153] op_sel_hi:[1,0]
	v_pk_mul_f32 v[8:9], v[8:9], v[152:153] op_sel_hi:[1,0]
	v_pk_mul_f32 v[6:7], v[6:7], v[152:153] op_sel_hi:[1,0]
	v_pk_mul_f32 v[4:5], v[4:5], v[152:153] op_sel_hi:[1,0]
	v_pk_mul_f32 v[2:3], v[2:3], v[152:153] op_sel_hi:[1,0]
	v_pk_mul_f32 v[0:1], v[0:1], v[152:153] op_sel_hi:[1,0]
	v_mul_f32_e32 v151, v151, v152
	v_mov_b32_e32 v152, v153

.LBB0_978:
	v_add3_u32 v32, s4, v147, v148
	ds_write_b128 v32, v[104:107]
	s_or_b64 exec, exec, s[66:67]
	s_and_saveexec_b64 s[66:67], s[12:13]
	s_cbranch_execnz .LBB0_963
	s_branch .LBB0_964

.LBB0_982:
	s_xor_b32 s4, s66, 1
	s_mulk_i32 s4, 0x5400
	s_add_i32 s4, s4, 0
	s_cmp_le_u32 s93, s60
	s_cbranch_scc0 .Lfl1_tail_b
	s_waitcnt vmcnt(4)
	s_branch .Lfl1_go_b

.Lfl1_go_b:
	s_and_saveexec_b64 s[66:67], s[8:9]
	s_cbranch_execz .LBB0_1007
	v_add3_u32 v32, s4, v144, v145
	ds_write_b128 v32, v[112:115]
	s_or_b64 exec, exec, s[66:67]
	s_and_saveexec_b64 s[66:67], s[10:11]
	s_cbranch_execnz .LBB0_1008

.LBB0_985:
	v_add3_u32 v32, s4, v149, v150
	ds_write_b128 v32, v[120:123]

.LBB0_993:
	s_cmp_gt_i32 s93, s50
	s_cbranch_scc1 .LBB0_998
	s_mul_i32 s4, s92, 0x5400
	s_add_i32 s24, s4, 0
	v_add3_u32 v153, s24, v192, v142
	ds_read_b128 v[32:35], v153
	ds_read_b128 v[36:39], v153 offset:32
	s_waitcnt lgkmcnt(1)
	v_mfma_f32_32x32x16_bf16 v[48:63], v[32:35], v[64:67], 0
	s_waitcnt lgkmcnt(0)
	v_mfma_f32_32x32x16_bf16 v[48:63], v[36:39], v[68:71], v[48:63]
	ds_read_b128 v[32:35], v153 offset:64
	ds_read_b128 v[36:39], v153 offset:96
	s_waitcnt lgkmcnt(1)
	v_mfma_f32_32x32x16_bf16 v[48:63], v[32:35], v[72:75], v[48:63]
	s_waitcnt lgkmcnt(0)
	v_mfma_f32_32x32x16_bf16 v[48:63], v[36:39], v[76:79], v[48:63]
	ds_read_b128 v[32:35], v153 offset:256
	ds_read_b128 v[36:39], v153 offset:288
	s_waitcnt lgkmcnt(1)
	v_mfma_f32_32x32x16_bf16 v[48:63], v[32:35], v[80:83], v[48:63]
	ds_read_b128 v[32:35], v153 offset:10752
	ds_read_b128 v[154:157], v153 offset:10784
	s_waitcnt lgkmcnt(2)
	v_mfma_f32_32x32x16_bf16 v[48:63], v[36:39], v[84:87], v[48:63]
	s_waitcnt lgkmcnt(1)
	v_mfma_f32_32x32x16_bf16 v[32:47], v[32:35], v[64:67], 0
	s_nop 9
	v_max_f32_e32 v162, v48, v48
	s_waitcnt lgkmcnt(0)
	v_mfma_f32_32x32x16_bf16 v[32:47], v[154:157], v[68:71], v[32:47]
	ds_read_b128 v[154:157], v153 offset:10816
	ds_read_b128 v[158:161], v153 offset:10848
	s_waitcnt lgkmcnt(1)
	v_mfma_f32_32x32x16_bf16 v[32:47], v[154:157], v[72:75], v[32:47]
	s_waitcnt lgkmcnt(0)
	v_mfma_f32_32x32x16_bf16 v[32:47], v[158:161], v[76:79], v[32:47]
	ds_read_b128 v[154:157], v153 offset:11008
	ds_read_b128 v[158:161], v153 offset:11040
	v_max_f32_e32 v153, v49, v49
	v_max_f32_e32 v153, v162, v153
	v_max3_f32 v153, v153, v50, v51
	v_max3_f32 v153, v153, v52, v53
	v_max3_f32 v153, v153, v54, v55
	v_max3_f32 v153, v153, v56, v57
	s_waitcnt lgkmcnt(1)
	v_mfma_f32_32x32x16_bf16 v[32:47], v[154:157], v[80:83], v[32:47]
	v_max3_f32 v153, v153, v58, v59
	v_max3_f32 v153, v153, v60, v61
	v_max3_f32 v153, v153, v62, v63
	s_waitcnt lgkmcnt(0)
	v_mfma_f32_32x32x16_bf16 v[32:47], v[158:161], v[84:87], v[32:47]
	s_nop 11
	v_max3_f32 v153, v153, v32, v33
	v_max3_f32 v153, v153, v34, v35
	v_max3_f32 v153, v153, v36, v37
	v_max3_f32 v153, v153, v38, v39
	v_max3_f32 v153, v153, v40, v41
	v_max3_f32 v153, v153, v42, v43
	v_max3_f32 v153, v153, v44, v45
	v_max3_f32 v153, v153, v46, v47
	v_mov_b32_e32 v154, v153
	s_nop 1
	v_permlane32_swap_b32_e32 v153, v154
	v_max_f32_e32 v154, v154, v154
	v_max_f32_e32 v153, v153, v153
	v_max_f32_e32 v153, v153, v154
	v_cmp_gt_f32_e32 vcc, v153, v152
	s_cbranch_vccz .LBB0_996
	v_max_f32_e32 v153, v153, v153
	v_max_f32_e32 v154, v152, v152
	v_max_f32_e32 v153, v154, v153
	v_sub_f32_e32 v152, v152, v153
	v_exp_f32_e32 v152, v152
	s_nop 0
	v_pk_mul_f32 v[30:31], v[30:31], v[152:153] op_sel_hi:[1,0]
	v_pk_mul_f32 v[28:29], v[28:29], v[152:153] op_sel_hi:[1,0]
	v_pk_mul_f32 v[26:27], v[26:27], v[152:153] op_sel_hi:[1,0]
	v_pk_mul_f32 v[24:25], v[24:25], v[152:153] op_sel_hi:[1,0]
	v_pk_mul_f32 v[22:23], v[22:23], v[152:153] op_sel_hi:[1,0]
	v_pk_mul_f32 v[20:21], v[20:21], v[152:153] op_sel_hi:[1,0]
	v_pk_mul_f32 v[18:19], v[18:19], v[152:153] op_sel_hi:[1,0]
	v_pk_mul_f32 v[16:17], v[16:17], v[152:153] op_sel_hi:[1,0]
	v_pk_mul_f32 v[14:15], v[14:15], v[152:153] op_sel_hi:[1,0]
	v_pk_mul_f32 v[12:13], v[12:13], v[152:153] op_sel_hi:[1,0]
	v_pk_mul_f32 v[10:11], v[10:11], v[152:153] op_sel_hi:[1,0]
	v_pk_mul_f32 v[8:9], v[8:9], v[152:153] op_sel_hi:[1,0]
	v_pk_mul_f32 v[6:7], v[6:7], v[152:153] op_sel_hi:[1,0]
	v_pk_mul_f32 v[4:5], v[4:5], v[152:153] op_sel_hi:[1,0]
	v_pk_mul_f32 v[2:3], v[2:3], v[152:153] op_sel_hi:[1,0]
	v_pk_mul_f32 v[0:1], v[0:1], v[152:153] op_sel_hi:[1,0]
	v_mul_f32_e32 v151, v151, v152
	v_mov_b32_e32 v152, v153

.LBB0_999:
	s_xor_b32 s4, s92, 1
	s_mulk_i32 s4, 0x5400
	s_add_i32 s4, s4, 0
	s_cmp_le_u32 s93, s60
	s_cbranch_scc0 .Lfl1_tail_c
	s_waitcnt vmcnt(4)
	s_branch .Lfl1_go_c

.Lfl1_go_c:
	s_and_saveexec_b64 s[66:67], s[8:9]
	s_cbranch_execz .LBB0_1011
	v_add3_u32 v32, s4, v144, v145
	ds_write_b128 v32, v[88:91]
	s_or_b64 exec, exec, s[66:67]
	s_and_saveexec_b64 s[66:67], s[10:11]
	s_cbranch_execnz .LBB0_1012

.LBB0_1002:
	v_add3_u32 v32, s4, v149, v150
	ds_write_b128 v32, v[96:99]

.LBB0_1008:
	v_add3_u32 v32, s4, v147, v148
	ds_write_b128 v32, v[116:119]
	s_or_b64 exec, exec, s[66:67]
	s_and_saveexec_b64 s[66:67], s[12:13]
	s_cbranch_execnz .LBB0_985
	s_branch .LBB0_986

.LBB0_1012:
	v_add3_u32 v32, s4, v147, v148
	ds_write_b128 v32, v[92:95]
	s_or_b64 exec, exec, s[66:67]
	s_and_saveexec_b64 s[66:67], s[12:13]
	s_cbranch_execnz .LBB0_1002
	s_branch .LBB0_1003
